# SSD waves 4-7 issue only the 11 row loads they consume (24 placeholder loads per wave-step removed, vmcnt waits re-derived)
# speedup vs baseline: 1.0118x; 1.0118x over previous
; __device__ __forceinline__ unsigned cvt_pk_bf16(float lo, float hi) { unsigned r; asm volatile("v_cvt_pk_bf16_f32 %0, %1, %2" : "=v"(r) : "v"(lo), "v"(hi)); return r; }
; __device__ __forceinline__ float bf2f(unsigned short b) { return __uint_as_float(((unsigned)b) << 16); }
; __device__ __forceinline__ float bflo(unsigned u) { return __uint_as_float(u << 16); }
; __device__ __forceinline__ float bfhi(unsigned u) { return __uint_as_float(u & 0xffff0000u); }
; __device__ __forceinline__ float siluf_(float v) { return v * __builtin_amdgcn_rcpf(1.0f + __expf(-v)); }
; __device__ __forceinline__ void ssd_item(const Params& p, LAS unsigned char* lds, int bl, int head, int dry) {
;     ...
;         { const int i = ti_d, pc = pc_d;
;           f32x16 accd, acco;
; #pragma unroll
;           for (int r = 0; r < 16; ++r) { accd[r] = 0.f; acco[r] = 0.f; }
;           accd = mma32_k(XT + pc * 32 * SLD, BMm + i * 32 * SLD, 2 * (i + 1), accd, lane);
;           acco = mma32_k8(SB + pc * 32 * SLD, CM + i * 32 * SLD, acco, lane);
;           const int l = i * 32 + cl; const float ecs = __expf(fcs[l]), dsc = Dh * __builtin_amdgcn_rcpf(fdt[l]);
;           bf16_t* zp = proj + (r0 + l) * PLD + COL_Z + head * 64 + pc * 32 + rsub;
; #pragma unroll
;           for (int g4 = 0; g4 < 4; ++g4) { float y[4];
; #pragma unroll
;               for (int e = 0; e < 4; ++e) { const int pp = pc * 32 + 8 * g4 + rsub + e; y[e] = accd[g4 * 4 + e] + ecs * acco[g4 * 4 + e] + dsc * bf2f(XT[pp * SLD + l]); }
;               const u32x2 z2 = zr[g4];
;               y[0] *= siluf_(bflo(z2.x)); y[1] *= siluf_(bfhi(z2.x)); y[2] *= siluf_(bflo(z2.y)); y[3] *= siluf_(bfhi(z2.y));
;               u32x2 o; o.x = cvt_pk_bf16(y[0], y[1]); o.y = cvt_pk_bf16(y[2], y[3]);
;               if (!dry) *(u32x2*)(zp + 8 * g4) = o; } }
.LBB0_223:
	s_or_b64 exec, exec, s[0:1]
	ds_read_b128 v[32:35], v174
	s_cmp_lt_u32 s98, 4
	s_cbranch_scc1 .Lzw_skip
	s_waitcnt vmcnt(11)
.Lzw_skip:
	s_waitcnt vmcnt(35)
	ds_read_b128 v[156:159], v174 offset:32
	ds_read_b128 v[36:39], v173
	ds_read_b128 v[194:197], v173 offset:32
	ds_read_b128 v[198:201], v174 offset:64
	ds_read_b128 v[202:205], v173 offset:64
	ds_read_b128 v[206:209], v174 offset:96
	ds_read_b128 v[210:213], v173 offset:96
	s_waitcnt lgkmcnt(5)
	v_mfma_f32_32x32x16_bf16 v[32:47], v[32:35], v[36:39], 0
	s_cmp_lg_u32 s62, 32
	s_mov_b32 s58, s62
	s_waitcnt lgkmcnt(4)
	v_mfma_f32_32x32x16_bf16 v[32:47], v[156:159], v[194:197], v[32:47]
	s_waitcnt lgkmcnt(2)
	v_mfma_f32_32x32x16_bf16 v[32:47], v[198:201], v[202:205], v[32:47]
	s_waitcnt lgkmcnt(0)
	v_mfma_f32_32x32x16_bf16 v[32:47], v[206:209], v[210:213], v[32:47]
	ds_read_b128 v[156:159], v174 offset:128
	ds_read_b128 v[194:197], v173 offset:128
	ds_read_b128 v[198:201], v174 offset:160
	ds_read_b128 v[202:205], v173 offset:160
	ds_read_b128 v[206:209], v174 offset:192
	ds_read_b128 v[210:213], v173 offset:192
	ds_read_b128 v[214:217], v174 offset:224
	ds_read_b128 v[236:239], v173 offset:224
	s_waitcnt lgkmcnt(6)
	v_mfma_f32_32x32x16_bf16 v[32:47], v[156:159], v[194:197], v[32:47]
	v_lshl_add_u32 v156, v76, 2, s63
	ds_read2st64_b32 v[156:157], v156 offset1:2
	v_lshl_add_u64 v[196:197], s[36:37], 0, v[76:77]
	v_mad_u64_u32 v[158:159], s[0:1], v196, s33, v[74:75]
	v_mov_b32_e32 v194, s63
	s_waitcnt lgkmcnt(0)
	v_mul_f32_e32 v156, 0x3fb8aa3b, v156
	v_mfma_f32_32x32x16_bf16 v[32:47], v[198:201], v[202:205], v[32:47]
	v_exp_f32_e32 v195, v156
	v_rcp_f32_e32 v156, v157
	ds_read_u16 v198, v190 offset:544
	v_mul_f32_e32 v157, v161, v156
	v_mov_b32_e32 v156, v159
	v_mfma_f32_32x32x16_bf16 v[32:47], v[206:209], v[210:213], v[32:47]
	v_mad_u64_u32 v[196:197], s[0:1], v197, s33, v[156:157]
	v_mov_b32_e32 v159, v196
	v_and_b32_e32 v196, 0xffff0000, v104
	v_mfma_f32_32x32x16_bf16 v[32:47], v[214:217], v[236:239], v[32:47]
	s_nop 11
	v_fmac_f32_e32 v16, v32, v195
	ds_read_u16 v32, v190
	v_fmac_f32_e32 v18, v34, v195
	v_lshlrev_b32_e32 v34, 16, v104
	v_fmac_f32_e32 v17, v33, v195
	ds_read_u16 v33, v190 offset:272
	v_fmac_f32_e32 v19, v35, v195
	s_waitcnt lgkmcnt(1)
	v_lshlrev_b32_e32 v35, 16, v32
	v_mul_f32_e32 v32, 0xbfb8aa3b, v34
	v_exp_f32_e32 v32, v32
	s_waitcnt lgkmcnt(0)
	v_lshlrev_b32_e32 v197, 16, v33
	ds_read_u16 v33, v190 offset:816
	v_fmac_f32_e32 v20, v36, v195
	v_add_f32_e32 v32, 1.0, v32
	v_rcp_f32_e32 v156, v32
	v_fmac_f32_e32 v21, v37, v195
	s_waitcnt lgkmcnt(0)
	v_lshlrev_b32_e32 v33, 16, v33
	v_fmac_f32_e32 v22, v38, v195
	v_pk_mul_f32 v[34:35], v[156:157], v[34:35]
	v_fmac_f32_e32 v23, v39, v195
	v_add_f32_e32 v16, v16, v35
	v_mul_f32_e32 v199, v34, v16
	v_mul_f32_e32 v16, 0xbfb8aa3b, v196
	v_exp_f32_e32 v16, v16
	v_fmac_f32_e32 v24, v40, v195
	v_fmac_f32_e32 v25, v41, v195
	v_fmac_f32_e32 v26, v42, v195
	v_add_f32_e32 v16, 1.0, v16
	v_rcp_f32_e32 v156, v16
	v_fmac_f32_e32 v27, v43, v195
	v_fmac_f32_e32 v28, v44, v195
	v_fmac_f32_e32 v29, v45, v195
	v_pk_mul_f32 v[34:35], v[156:157], v[196:197]
	v_fmac_f32_e32 v30, v46, v195
	v_add_f32_e32 v16, v17, v35
	v_mul_f32_e32 v34, v34, v16
	v_lshlrev_b32_e32 v16, 16, v105
	v_mul_f32_e32 v32, 0xbfb8aa3b, v16
	v_exp_f32_e32 v32, v32
	v_lshlrev_b32_e32 v17, 16, v198
	v_fmac_f32_e32 v31, v47, v195
	v_add_f32_e32 v32, 1.0, v32
	v_rcp_f32_e32 v156, v32
	v_and_b32_e32 v32, 0xffff0000, v105
	v_pk_mul_f32 v[16:17], v[156:157], v[16:17]
	s_nop 0
	v_add_f32_e32 v17, v18, v17
	v_mul_f32_e32 v18, v16, v17
	v_mul_f32_e32 v16, 0xbfb8aa3b, v32
	v_exp_f32_e32 v16, v16
	s_nop 0
	v_add_f32_e32 v16, 1.0, v16
	v_rcp_f32_e32 v156, v16
	s_nop 0
	v_pk_mul_f32 v[16:17], v[156:157], v[32:33]
	s_nop 0
	v_add_f32_e32 v17, v19, v17
	v_mul_f32_e32 v17, v16, v17
	v_cvt_pk_bf16_f32 v16, v199, v34
	v_cvt_pk_bf16_f32 v17, v18, v17
	global_store_dwordx2 v[158:159], v[16:17], off
	ds_read_u16 v16, v190 offset:2176
	ds_read_u16 v17, v190 offset:2448
	ds_read_u16 v18, v190 offset:2720
	ds_read_u16 v19, v190 offset:2992
	v_lshlrev_b32_e32 v32, 16, v98
	s_waitcnt lgkmcnt(3)
	v_lshlrev_b32_e32 v33, 16, v16
	v_mul_f32_e32 v16, 0xbfb8aa3b, v32
	v_exp_f32_e32 v16, v16
	s_waitcnt lgkmcnt(2)
	v_lshlrev_b32_e32 v17, 16, v17
	s_waitcnt lgkmcnt(0)
	v_lshlrev_b32_e32 v19, 16, v19
	v_add_f32_e32 v16, 1.0, v16
	v_rcp_f32_e32 v156, v16
	s_nop 0
	v_pk_mul_f32 v[32:33], v[156:157], v[32:33]
	s_nop 0
	v_add_f32_e32 v16, v20, v33
	v_mul_f32_e32 v20, v32, v16
	v_and_b32_e32 v16, 0xffff0000, v98
	v_mul_f32_e32 v32, 0xbfb8aa3b, v16
	v_exp_f32_e32 v32, v32
	s_nop 0
	v_add_f32_e32 v32, 1.0, v32
	v_rcp_f32_e32 v156, v32
	s_nop 0
	v_pk_mul_f32 v[16:17], v[156:157], v[16:17]
	s_nop 0
	v_add_f32_e32 v17, v21, v17
	v_mul_f32_e32 v21, v16, v17
	v_lshlrev_b32_e32 v16, 16, v99
	v_lshlrev_b32_e32 v17, 16, v18
	v_mul_f32_e32 v18, 0xbfb8aa3b, v16
	v_exp_f32_e32 v18, v18
	s_nop 0
	v_add_f32_e32 v18, 1.0, v18
	v_rcp_f32_e32 v156, v18
	v_and_b32_e32 v18, 0xffff0000, v99
	v_pk_mul_f32 v[16:17], v[156:157], v[16:17]
	s_nop 0
	v_add_f32_e32 v17, v22, v17
	v_mul_f32_e32 v22, v16, v17
	v_mul_f32_e32 v16, 0xbfb8aa3b, v18
	v_exp_f32_e32 v16, v16
	s_nop 0
	v_add_f32_e32 v16, 1.0, v16
	v_rcp_f32_e32 v156, v16
	s_nop 0
	v_pk_mul_f32 v[16:17], v[156:157], v[18:19]
	s_nop 0
	v_add_f32_e32 v17, v23, v17
	v_mul_f32_e32 v17, v16, v17
	v_cvt_pk_bf16_f32 v16, v20, v21
	v_cvt_pk_bf16_f32 v17, v22, v17
	global_store_dwordx2 v[158:159], v[16:17], off offset:16
	ds_read_u16 v16, v190 offset:4352
	ds_read_u16 v17, v190 offset:4624
	ds_read_u16 v18, v190 offset:4896
	ds_read_u16 v19, v190 offset:5168
	v_lshlrev_b32_e32 v20, 16, v96
	s_waitcnt lgkmcnt(3)
; __device__ __forceinline__ unsigned cvt_pk_bf16(float lo, float hi) { unsigned r; asm volatile("v_cvt_pk_bf16_f32 %0, %1, %2" : "=v"(r) : "v"(lo), "v"(hi)); return r; }
; __device__ __forceinline__ float bf2f(unsigned short b) { return __uint_as_float(((unsigned)b) << 16); }
; __device__ __forceinline__ float bflo(unsigned u) { return __uint_as_float(u << 16); }
; __device__ __forceinline__ float bfhi(unsigned u) { return __uint_as_float(u & 0xffff0000u); }
; __device__ __forceinline__ float siluf_(float v) { return v * __builtin_amdgcn_rcpf(1.0f + __expf(-v)); }
; __device__ __forceinline__ void ssd_item(const Params& p, LAS unsigned char* lds, int bl, int head, int dry) {
;     ...
;           for (int g4 = 0; g4 < 4; ++g4) { float y[4];
; #pragma unroll
;               for (int e = 0; e < 4; ++e) { const int pp = pc * 32 + 8 * g4 + rsub + e; y[e] = accd[g4 * 4 + e] + ecs * acco[g4 * 4 + e] + dsc * bf2f(XT[pp * SLD + l]); }
;               const u32x2 z2 = zr[g4];
;               y[0] *= siluf_(bflo(z2.x)); y[1] *= siluf_(bfhi(z2.x)); y[2] *= siluf_(bflo(z2.y)); y[3] *= siluf_(bfhi(z2.y));
;               u32x2 o; o.x = cvt_pk_bf16(y[0], y[1]); o.y = cvt_pk_bf16(y[2], y[3]);
;               if (!dry) *(u32x2*)(zp + 8 * g4) = o; } }
;         { const float cd = __expf(fcs[127]);
; #pragma unroll
;           for (int r = 0; r < 16; ++r) accS[r] *= cd;
;           accS = mma32_k8(XT + pt * 32 * SLD, BT + nt * 32 * SLD, accS, lane); }
;     }
	v_lshlrev_b32_e32 v21, 16, v16
	v_mul_f32_e32 v16, 0xbfb8aa3b, v20
	v_exp_f32_e32 v16, v16
	s_waitcnt lgkmcnt(2)
	v_lshlrev_b32_e32 v17, 16, v17
	s_waitcnt lgkmcnt(0)
	v_lshlrev_b32_e32 v19, 16, v19
	v_add_f32_e32 v16, 1.0, v16
	v_rcp_f32_e32 v156, v16
	s_nop 0
	v_pk_mul_f32 v[20:21], v[156:157], v[20:21]
	s_nop 0
	v_add_f32_e32 v16, v24, v21
	v_mul_f32_e32 v20, v20, v16
	v_and_b32_e32 v16, 0xffff0000, v96
	v_mul_f32_e32 v21, 0xbfb8aa3b, v16
	v_exp_f32_e32 v21, v21
	s_nop 0
	v_add_f32_e32 v21, 1.0, v21
	v_rcp_f32_e32 v156, v21
	s_nop 0
	v_pk_mul_f32 v[16:17], v[156:157], v[16:17]
	s_nop 0
	v_add_f32_e32 v17, v25, v17
	v_mul_f32_e32 v21, v16, v17
	v_lshlrev_b32_e32 v16, 16, v97
	v_lshlrev_b32_e32 v17, 16, v18
	v_mul_f32_e32 v18, 0xbfb8aa3b, v16
	v_exp_f32_e32 v18, v18
	s_nop 0
	v_add_f32_e32 v18, 1.0, v18
	v_rcp_f32_e32 v156, v18
	v_and_b32_e32 v18, 0xffff0000, v97
	v_pk_mul_f32 v[16:17], v[156:157], v[16:17]
	s_nop 0
	v_add_f32_e32 v17, v26, v17
	v_mul_f32_e32 v22, v16, v17
	v_mul_f32_e32 v16, 0xbfb8aa3b, v18
	v_exp_f32_e32 v16, v16
	s_nop 0
	v_add_f32_e32 v16, 1.0, v16
	v_rcp_f32_e32 v156, v16
	s_nop 0
	v_pk_mul_f32 v[16:17], v[156:157], v[18:19]
	s_nop 0
	v_add_f32_e32 v17, v27, v17
	v_mul_f32_e32 v17, v16, v17
	v_cvt_pk_bf16_f32 v16, v20, v21
	v_cvt_pk_bf16_f32 v17, v22, v17
	global_store_dwordx2 v[158:159], v[16:17], off offset:32
	ds_read_u16 v16, v190 offset:6528
	ds_read_u16 v17, v190 offset:6800
	ds_read_u16 v18, v190 offset:7072
	ds_read_u16 v19, v190 offset:7344
	v_lshlrev_b32_e32 v20, 16, v90
	s_waitcnt lgkmcnt(3)
	v_lshlrev_b32_e32 v21, 16, v16
	v_mul_f32_e32 v16, 0xbfb8aa3b, v20
	v_exp_f32_e32 v16, v16
	s_waitcnt lgkmcnt(2)
	v_lshlrev_b32_e32 v17, 16, v17
	s_waitcnt lgkmcnt(0)
	v_lshlrev_b32_e32 v19, 16, v19
	v_add_f32_e32 v16, 1.0, v16
	v_rcp_f32_e32 v156, v16
	s_nop 0
	v_pk_mul_f32 v[20:21], v[156:157], v[20:21]
	s_nop 0
	v_add_f32_e32 v16, v28, v21
	v_mul_f32_e32 v20, v20, v16
	v_and_b32_e32 v16, 0xffff0000, v90
	v_mul_f32_e32 v21, 0xbfb8aa3b, v16
	v_exp_f32_e32 v21, v21
	s_nop 0
	v_add_f32_e32 v21, 1.0, v21
	v_rcp_f32_e32 v156, v21
	s_nop 0
	v_pk_mul_f32 v[16:17], v[156:157], v[16:17]
	s_nop 0
	v_add_f32_e32 v17, v29, v17
	v_mul_f32_e32 v21, v16, v17
	v_lshlrev_b32_e32 v16, 16, v91
	v_lshlrev_b32_e32 v17, 16, v18
	v_mul_f32_e32 v18, 0xbfb8aa3b, v16
	v_exp_f32_e32 v18, v18
	s_nop 0
	v_add_f32_e32 v18, 1.0, v18
	v_rcp_f32_e32 v156, v18
	v_and_b32_e32 v18, 0xffff0000, v91
	v_pk_mul_f32 v[16:17], v[156:157], v[16:17]
	s_nop 0
	v_add_f32_e32 v17, v30, v17
	v_mul_f32_e32 v22, v16, v17
	v_mul_f32_e32 v16, 0xbfb8aa3b, v18
	v_exp_f32_e32 v16, v16
	s_nop 0
	v_add_f32_e32 v16, 1.0, v16
	v_rcp_f32_e32 v156, v16
	s_nop 0
	v_pk_mul_f32 v[16:17], v[156:157], v[18:19]
	s_nop 0
	v_add_f32_e32 v17, v31, v17
	v_mul_f32_e32 v17, v16, v17
	v_cvt_pk_bf16_f32 v16, v20, v21
	v_cvt_pk_bf16_f32 v17, v22, v17
	global_store_dwordx2 v[158:159], v[16:17], off offset:48
	ds_read_b32 v16, v194 offset:508
	s_waitcnt lgkmcnt(0)
	v_mul_f32_e32 v16, 0x3fb8aa3b, v16
	v_exp_f32_e32 v16, v16
	s_nop 0
	v_pk_mul_f32 v[14:15], v[14:15], v[16:17] op_sel_hi:[1,0]
	v_pk_mul_f32 v[12:13], v[12:13], v[16:17] op_sel_hi:[1,0]
	v_pk_mul_f32 v[10:11], v[10:11], v[16:17] op_sel_hi:[1,0]
	v_pk_mul_f32 v[8:9], v[8:9], v[16:17] op_sel_hi:[1,0]
	v_pk_mul_f32 v[6:7], v[6:7], v[16:17] op_sel_hi:[1,0]
	v_pk_mul_f32 v[4:5], v[4:5], v[16:17] op_sel_hi:[1,0]
	v_pk_mul_f32 v[2:3], v[2:3], v[16:17] op_sel_hi:[1,0]
	v_pk_mul_f32 v[0:1], v[0:1], v[16:17] op_sel_hi:[1,0]
	ds_read_b128 v[16:19], v175
	ds_read_b128 v[20:23], v175 offset:32
	ds_read_b128 v[24:27], v176
	ds_read_b128 v[28:31], v176 offset:32
	ds_read_b128 v[32:35], v175 offset:64
	ds_read_b128 v[36:39], v176 offset:64
	ds_read_b128 v[40:43], v175 offset:96
	ds_read_b128 v[44:47], v176 offset:96
	s_waitcnt lgkmcnt(5)
	v_mfma_f32_32x32x16_bf16 v[0:15], v[16:19], v[24:27], v[0:15]
	s_waitcnt lgkmcnt(4)
	v_mfma_f32_32x32x16_bf16 v[0:15], v[20:23], v[28:31], v[0:15]
	s_waitcnt lgkmcnt(2)
	v_mfma_f32_32x32x16_bf16 v[0:15], v[32:35], v[36:39], v[0:15]
	s_waitcnt lgkmcnt(0)
	v_mfma_f32_32x32x16_bf16 v[0:15], v[40:43], v[44:47], v[0:15]
	ds_read_b128 v[16:19], v175 offset:128
	ds_read_b128 v[20:23], v176 offset:128
	ds_read_b128 v[24:27], v175 offset:160
	ds_read_b128 v[28:31], v176 offset:160
	ds_read_b128 v[32:35], v175 offset:192
	ds_read_b128 v[36:39], v176 offset:192
	ds_read_b128 v[40:43], v175 offset:224
	ds_read_b128 v[44:47], v176 offset:224
	s_waitcnt lgkmcnt(6)
	v_mfma_f32_32x32x16_bf16 v[0:15], v[16:19], v[20:23], v[0:15]
	s_waitcnt lgkmcnt(4)
	v_mfma_f32_32x32x16_bf16 v[0:15], v[24:27], v[28:31], v[0:15]
	s_waitcnt lgkmcnt(2)
	v_mfma_f32_32x32x16_bf16 v[0:15], v[32:35], v[36:39], v[0:15]
	s_waitcnt lgkmcnt(0)
	v_mfma_f32_32x32x16_bf16 v[0:15], v[40:43], v[44:47], v[0:15]
	s_cbranch_scc0 .LBB0_203
; __device__ __forceinline__ unsigned short f2bf(float f) { return (unsigned short)(cvt_pk_bf16(f, 0.f) & 0xffffu); }
; #define SSD_ISSUE_DT(c_) do { const int c__ = (c_); const float* dp = dtraw + (rowbase + (size_t)c__ * 128 + lane) * 32 + head; dtn0 = dp[0]; dtn1 = dp[64 * 32]; } while (0)
; __device__ __forceinline__ void ssd_item(const Params& p, LAS unsigned char* lds, int bl, int head, int dry) {
;     ...
;         __syncthreads();
; #pragma unroll
;         for (int r = 0; r < 16; ++r) { const int row = (r & 3) + 8 * (r >> 2) + rsub; SB[(pt * 32 + row) * SLD + nt * 32 + cl] = f2bf(accS[r]); }
;         { const bf16_t* zp = proj + (r0 + ti_d * 32 + cl) * PLD + COL_Z + head * 64 + pc_d * 32 + rsub;
; #pragma unroll
;           for (int g4 = 0; g4 < 4; ++g4) zr[g4] = *(const u32x2*)(zp + 8 * g4); }
;         SSD_ISSUE_DT(c + 1 < 32 ? c + 1 : 31);
;         __builtin_amdgcn_sched_barrier(0);
;         if (cact) {
.LBB0_224:
	s_waitcnt lgkmcnt(0)
	s_barrier
	v_cvt_pk_bf16_f32 v16, v0, v185
	ds_write_b16 v186, v16
	v_cvt_pk_bf16_f32 v16, v1, v185
	ds_write_b16 v186, v16 offset:272
	v_cvt_pk_bf16_f32 v16, v2, v185
	ds_write_b16 v186, v16 offset:544
	v_cvt_pk_bf16_f32 v16, v3, v185
	ds_write_b16 v186, v16 offset:816
	v_cvt_pk_bf16_f32 v16, v4, v185
	ds_write_b16 v186, v16 offset:2176
	v_cvt_pk_bf16_f32 v16, v5, v185
	ds_write_b16 v186, v16 offset:2448
	v_cvt_pk_bf16_f32 v16, v6, v185
	ds_write_b16 v186, v16 offset:2720
	v_cvt_pk_bf16_f32 v16, v7, v185
	ds_write_b16 v186, v16 offset:2992
	v_cvt_pk_bf16_f32 v16, v8, v185
	ds_write_b16 v186, v16 offset:4352
	v_cvt_pk_bf16_f32 v16, v9, v185
	ds_write_b16 v186, v16 offset:4624
	v_cvt_pk_bf16_f32 v16, v10, v185
	ds_write_b16 v186, v16 offset:4896
	v_cvt_pk_bf16_f32 v16, v11, v185
	ds_write_b16 v186, v16 offset:5168
	v_cvt_pk_bf16_f32 v16, v12, v185
	s_lshl_b32 s0, s58, 7
	ds_write_b16 v186, v16 offset:6528
	v_cvt_pk_bf16_f32 v16, v13, v185
	s_bitcmp1_b32 s58, 0
	ds_write_b16 v186, v16 offset:6800
	v_cvt_pk_bf16_f32 v16, v14, v185
	s_cselect_b32 s1, 0x600, 0
	ds_write_b16 v186, v16 offset:7072
	v_cvt_pk_bf16_f32 v16, v15, v185
	s_or_b32 s36, s54, s0
	s_mov_b32 s37, s55
	ds_write_b16 v186, v16 offset:7344
	v_lshl_add_u64 v[16:17], v[72:73], 0, s[36:37]
	s_add_i32 s63, s1, 0
	v_mad_u64_u32 v[18:19], s[0:1], v16, s33, v[74:75]
	s_add_i32 s62, s58, 1
	s_add_i32 s63, s63, 0x22000
	v_mov_b32_e32 v16, v19
	s_lshl_b32 s2, s62, 7
	v_mad_u64_u32 v[16:17], s[0:1], v17, s33, v[16:17]
	s_cmp_eq_u32 s58, 31
	s_cselect_b64 s[0:1], -1, 0
	s_and_b64 s[56:57], s[0:1], exec
	s_cselect_b32 s2, 0xf80, s2
	v_mov_b32_e32 v19, v16
	v_lshl_add_u64 v[16:17], v[70:71], 0, s[2:3]
	v_lshlrev_b64 v[16:17], 7, v[16:17]
	v_lshl_add_u64 v[16:17], s[52:53], 0, v[16:17]
	global_load_dwordx2 v[104:105], v[18:19], off
	global_load_dwordx2 v[98:99], v[18:19], off offset:16
	global_load_dwordx2 v[96:97], v[18:19], off offset:32
	global_load_dwordx2 v[90:91], v[18:19], off offset:48
	global_load_dword v157, v[16:17], off
	v_add_co_u32_e32 v16, vcc, 0x2000, v16
	s_nop 1
	v_addc_co_u32_e32 v17, vcc, 0, v17, vcc
	global_load_dword v156, v[16:17], off
	v_mov_b32_e32 v16, 0
	s_and_saveexec_b64 s[56:57], s[40:41]
	s_cbranch_execz .LBB0_242
	s_cmp_lt_u32 s98, 4
	s_cbranch_scc1 .Lcw_skip
	s_waitcnt vmcnt(6)

; #define LAS __attribute__((address_space(3)))
; __device__ __forceinline__ f32x16 mma32_k8(const LAS bf16_t* A, const LAS bf16_t* B, f32x16 acc, int lane) {
;     const LAS bf16_t* ap = A + (lane & 31) * SLD + (lane >> 5) * 8; const LAS bf16_t* bp = B + (lane & 31) * SLD + (lane >> 5) * 8;
; #pragma unroll
;     for (int h = 0; h < 2; ++h) {
;         bf16x8 a[4], b[4];
; #pragma unroll
;         for (int ks = 0; ks < 4; ++ks) { a[ks] = *(const LAS bf16x8*)(ap + (h * 4 + ks) * 16); b[ks] = *(const LAS bf16x8*)(bp + (h * 4 + ks) * 16); }
; #pragma unroll
;         for (int ks = 0; ks < 4; ++ks) acc = __builtin_amdgcn_mfma_f32_32x32x16_bf16(a[ks], b[ks], acc, 0, 0, 0);
;     }
;     return acc;
; }
.LBB0_242:
	s_or_b64 exec, exec, s[56:57]
	v_max_i32_e32 v17, 0, v16
	v_mad_u64_u32 v[18:19], s[56:57], v17, s33, v[68:69]
	v_max_i32_e32 v17, -1, v16
	v_add_u32_e32 v17, 1, v17
	v_mad_u64_u32 v[20:21], s[56:57], v17, s33, v[68:69]
	v_max_i32_e32 v17, -2, v16
	v_add_u32_e32 v17, 2, v17
	v_add_u32_e32 v16, 3, v16
	v_mad_u64_u32 v[22:23], s[56:57], v17, s33, v[68:69]
	v_mad_i64_i32 v[16:17], s[56:57], v16, s33, v[68:69]
	global_load_dwordx2 v[150:151], v[18:19], off
	global_load_dwordx2 v[152:153], v[20:21], off
	global_load_dwordx2 v[154:155], v[22:23], off
	global_load_dwordx2 v[148:149], v[16:17], off
	v_lshl_add_u64 v[16:17], v[16:17], 0, v[168:169]
	v_lshl_add_u64 v[18:19], v[16:17], 0, v[168:169]
	v_lshl_add_u64 v[20:21], v[18:19], 0, v[168:169]
	global_load_dwordx2 v[146:147], v[16:17], off
	global_load_dwordx2 v[144:145], v[18:19], off
	global_load_dwordx2 v[142:143], v[20:21], off
	v_lshl_add_u64 v[16:17], v[20:21], 0, v[168:169]
	global_load_dwordx2 v[140:141], v[16:17], off
	v_lshl_add_u64 v[16:17], v[16:17], 0, v[168:169]
	global_load_dwordx2 v[138:139], v[16:17], off
	v_lshl_add_u64 v[16:17], v[16:17], 0, v[168:169]
	global_load_dwordx2 v[136:137], v[16:17], off
	v_lshl_add_u64 v[16:17], v[16:17], 0, v[168:169]
	global_load_dwordx2 v[134:135], v[16:17], off
	s_cmp_ge_u32 s98, 4
	s_cbranch_scc1 .Lrows_done
	v_lshl_add_u64 v[16:17], v[16:17], 0, v[246:247]
	global_load_dwordx2 v[132:133], v[16:17], off
	v_lshl_add_u64 v[16:17], v[16:17], 0, v[246:247]
	global_load_dwordx2 v[130:131], v[16:17], off
	v_lshl_add_u64 v[16:17], v[16:17], 0, v[246:247]
	global_load_dwordx2 v[128:129], v[16:17], off
	v_lshl_add_u64 v[16:17], v[16:17], 0, v[246:247]
	global_load_dwordx2 v[126:127], v[16:17], off
	v_lshl_add_u64 v[16:17], v[16:17], 0, v[246:247]
	global_load_dwordx2 v[124:125], v[16:17], off
	v_lshl_add_u64 v[16:17], v[16:17], 0, v[246:247]
	global_load_dwordx2 v[122:123], v[16:17], off
	v_lshl_add_u64 v[16:17], v[16:17], 0, v[246:247]
	global_load_dwordx2 v[120:121], v[16:17], off
	v_lshl_add_u64 v[16:17], v[16:17], 0, v[246:247]
	global_load_dwordx2 v[118:119], v[16:17], off
	v_lshl_add_u64 v[16:17], v[16:17], 0, v[246:247]
	global_load_dwordx2 v[116:117], v[16:17], off
	v_lshl_add_u64 v[16:17], v[16:17], 0, v[246:247]
	global_load_dwordx2 v[114:115], v[16:17], off
	v_lshl_add_u64 v[16:17], v[16:17], 0, v[246:247]
	global_load_dwordx2 v[112:113], v[16:17], off
	v_lshl_add_u64 v[16:17], v[16:17], 0, v[246:247]
	global_load_dwordx2 v[110:111], v[16:17], off
	v_lshl_add_u64 v[16:17], v[16:17], 0, v[246:247]
	global_load_dwordx2 v[108:109], v[16:17], off
	v_lshl_add_u64 v[16:17], v[16:17], 0, v[246:247]
	global_load_dwordx2 v[106:107], v[16:17], off
	v_lshl_add_u64 v[16:17], v[16:17], 0, v[246:247]
	global_load_dwordx2 v[102:103], v[16:17], off
	v_lshl_add_u64 v[16:17], v[16:17], 0, v[246:247]
	global_load_dwordx2 v[100:101], v[16:17], off
	v_lshl_add_u64 v[16:17], v[16:17], 0, v[246:247]
	global_load_dwordx2 v[94:95], v[16:17], off
	v_lshl_add_u64 v[16:17], v[16:17], 0, v[246:247]
	global_load_dwordx2 v[92:93], v[16:17], off
	v_lshl_add_u64 v[16:17], v[16:17], 0, v[246:247]
	global_load_dwordx2 v[88:89], v[16:17], off
	v_lshl_add_u64 v[16:17], v[16:17], 0, v[246:247]
	global_load_dwordx2 v[86:87], v[16:17], off
	v_lshl_add_u64 v[16:17], v[16:17], 0, v[246:247]
	global_load_dwordx2 v[84:85], v[16:17], off
	v_lshl_add_u64 v[16:17], v[16:17], 0, v[246:247]
	global_load_dwordx2 v[82:83], v[16:17], off
	v_lshl_add_u64 v[16:17], v[16:17], 0, v[246:247]
	global_load_dwordx2 v[80:81], v[16:17], off
	v_lshl_add_u64 v[16:17], v[16:17], 0, v[246:247]
	global_load_dwordx2 v[78:79], v[16:17], off
.Lrows_done:
	v_mov_b32_e32 v16, 0
	v_mov_b32_e32 v32, 0
	v_mov_b32_e32 v33, 0
	v_mov_b32_e32 v34, 0
	v_mov_b32_e32 v35, 0
	v_mov_b32_e32 v36, 0
	v_mov_b32_e32 v37, 0
	v_mov_b32_e32 v38, 0
	v_mov_b32_e32 v39, 0
	v_mov_b32_e32 v40, 0
	v_mov_b32_e32 v41, 0
	v_mov_b32_e32 v42, 0
	v_mov_b32_e32 v43, 0
	v_mov_b32_e32 v44, 0
	v_mov_b32_e32 v45, 0
	v_mov_b32_e32 v46, 0
	v_mov_b32_e32 v47, 0
	s_waitcnt lgkmcnt(0)
	s_barrier
	s_and_saveexec_b64 s[56:57], s[46:47]
	s_cbranch_execz .LBB0_244
	ds_read_b128 v[16:19], v188
	ds_read_b128 v[194:197], v171 offset:34816
	ds_read_b128 v[20:23], v188 offset:32
	ds_read_b128 v[198:201], v171 offset:34848
	ds_read_b128 v[24:27], v188 offset:64
	ds_read_b128 v[202:205], v171 offset:34880
	ds_read_b128 v[28:31], v188 offset:96
	ds_read_b128 v[206:209], v171 offset:34912
	s_waitcnt lgkmcnt(6)
	v_mfma_f32_32x32x16_bf16 v[32:47], v[16:19], v[194:197], 0
	ds_read_b128 v[16:19], v188 offset:128
	ds_read_b128 v[194:197], v171 offset:34944
	s_waitcnt lgkmcnt(6)
	v_mfma_f32_32x32x16_bf16 v[32:47], v[20:23], v[198:201], v[32:47]
	ds_read_b128 v[20:23], v188 offset:160
	ds_read_b128 v[198:201], v171 offset:34976
	s_waitcnt lgkmcnt(6)
	v_mfma_f32_32x32x16_bf16 v[32:47], v[24:27], v[202:205], v[32:47]
	ds_read_b128 v[24:27], v188 offset:192
	ds_read_b128 v[202:205], v171 offset:35008
	s_waitcnt lgkmcnt(6)
	v_mfma_f32_32x32x16_bf16 v[32:47], v[28:31], v[206:209], v[32:47]
	ds_read_b128 v[28:31], v188 offset:224
	ds_read_b128 v[206:209], v171 offset:35040
	s_waitcnt lgkmcnt(6)
	v_mfma_f32_32x32x16_bf16 v[32:47], v[16:19], v[194:197], v[32:47]
	s_waitcnt lgkmcnt(4)
	v_mfma_f32_32x32x16_bf16 v[32:47], v[20:23], v[198:201], v[32:47]
	s_waitcnt lgkmcnt(2)
	v_mfma_f32_32x32x16_bf16 v[32:47], v[24:27], v[202:205], v[32:47]
	s_waitcnt lgkmcnt(0)
	v_mfma_f32_32x32x16_bf16 v[32:47], v[28:31], v[206:209], v[32:47]

.LBB0_315:
	s_waitcnt vmcnt(12)
	v_add_f32_e32 v16, v162, v157
	s_mov_b32 s0, 0x41a00000
	v_cmp_nlt_f32_e32 vcc, s0, v16
	s_and_saveexec_b64 s[58:59], vcc
	s_cbranch_execz .LBB0_319
	v_mul_f32_e32 v16, 0x3fb8aa3b, v16
	v_exp_f32_e32 v16, v16
	s_mov_b32 s0, 0x38d1b717
	v_cmp_ngt_f32_e32 vcc, s0, v16
	s_and_saveexec_b64 s[60:61], vcc
	s_cbranch_execz .LBB0_318
	v_add_f32_e32 v16, 1.0, v16
	s_mov_b32 s0, 0x800000
	v_cmp_gt_f32_e32 vcc, s0, v16
	s_mov_b32 s0, 0x3f317217
	s_nop 0
	v_cndmask_b32_e64 v17, 0, 32, vcc
	v_ldexp_f32 v16, v16, v17
	v_log_f32_e32 v16, v16
	s_nop 0
	v_mul_f32_e32 v17, 0x3f317217, v16
	v_fma_f32 v17, v16, s0, -v17
	v_fmac_f32_e32 v17, 0x3377d1cf, v16
	s_mov_b32 s0, 0x7f800000
	v_fmac_f32_e32 v17, 0x3f317217, v16
	v_cmp_lt_f32_e64 s[0:1], |v16|, s0
	s_nop 1
	v_cndmask_b32_e64 v16, v16, v17, s[0:1]
	v_cndmask_b32_e32 v17, 0, v227, vcc
	v_sub_f32_e32 v16, v16, v17

.LBB0_319:
	s_or_b64 exec, exec, s[58:59]
	s_waitcnt vmcnt(11)
	v_add_f32_e32 v17, v162, v156
	s_mov_b32 s0, 0x41a00000
	v_cmp_nlt_f32_e32 vcc, s0, v17
	s_and_saveexec_b64 s[58:59], vcc
	s_cbranch_execz .LBB0_323
	v_mul_f32_e32 v17, 0x3fb8aa3b, v17
	v_exp_f32_e32 v17, v17
	s_mov_b32 s0, 0x38d1b717
	v_cmp_ngt_f32_e32 vcc, s0, v17
	s_and_saveexec_b64 s[60:61], vcc
	s_cbranch_execz .LBB0_322
	v_add_f32_e32 v17, 1.0, v17
	s_mov_b32 s0, 0x800000
	v_cmp_gt_f32_e32 vcc, s0, v17
	s_mov_b32 s0, 0x3f317217
	s_nop 0
	v_cndmask_b32_e64 v18, 0, 32, vcc
	v_ldexp_f32 v17, v17, v18
	v_log_f32_e32 v17, v17
	s_nop 0
	v_mul_f32_e32 v18, 0x3f317217, v17
	v_fma_f32 v18, v17, s0, -v18
	v_fmac_f32_e32 v18, 0x3377d1cf, v17
	s_mov_b32 s0, 0x7f800000
	v_fmac_f32_e32 v18, 0x3f317217, v17
	v_cmp_lt_f32_e64 s[0:1], |v17|, s0
	s_nop 1
	v_cndmask_b32_e64 v17, v17, v18, s[0:1]
	v_cndmask_b32_e32 v18, 0, v227, vcc
	v_sub_f32_e32 v17, v17, v18
